# DG: BI version plus a guard that falls back to grid-stride prep in phase 0 (and disables the deferred-prep hooks) when the grid is not 256 workgroups
# speedup vs baseline: 1.0080x; 1.0010x over previous
; __device__ void phase_prep(const Params& p, LAS unsigned char* lds) {
;     ...
;     constexpr int I_TR = 2 * T_L, I_POOL = I_TR + 128, I_FOUR = I_POOL + 256, I_MOD = I_FOUR + 192, I_ALL = I_MOD + 1;
;     for (int prep_rep = 0; prep_rep < ((PROBE >= 301 && PROBE <= 304) ? 2 : 1); ++prep_rep)
;     for (int it = blockIdx.x; it < I_ALL; it += gridDim.x) {
;     ...
;         if (prep_rep == 1) { const int cls = (it < I_TR) ? 301 : (it < I_FOUR) ? 302 : (it < I_MOD) ? 303 : 304; if (cls != PROBE) continue; }
;     ...
;         if (it < I_TR) {
.LBB0_14:
	s_andn2_b64 vcc, exec, s[0:1]
	s_cbranch_vccnz .LBB0_735
	s_cmpk_eq_u32 s72, 0x100
	s_cbranch_scc1 .Lmy_dp_g256
	v_writelane_b32 v252, s26, 1
	v_writelane_b32 v252, s72, 2
	s_movk_i32 s1, 2369
	v_writelane_b32 v252, s1, 3
	s_movk_i32 s1, 0
	v_writelane_b32 v252, s1, 0
	s_movk_i32 s1, 0x7fff
	v_writelane_b32 v252, s1, 5
	s_branch .LBB0_650
.Lmy_dp_g256:
	v_writelane_b32 v252, s26, 1
	s_movk_i32 s1, 256
	v_writelane_b32 v252, s1, 2
	s_movk_i32 s1, 369
	v_writelane_b32 v252, s1, 3
	s_movk_i32 s1, 0
	v_writelane_b32 v252, s1, 0
	s_movk_i32 s1, 113
	v_writelane_b32 v252, s1, 5
	s_movk_i32 s1, 2063
	v_writelane_b32 v252, s1, 6
	s_movk_i32 s1, 209
	v_writelane_b32 v252, s1, 7
	s_movk_i32 s1, -96
	v_writelane_b32 v252, s1, 8
	s_movk_i32 s1, 368
	v_writelane_b32 v252, s1, 9
	s_movk_i32 s1, 2000
	v_writelane_b32 v252, s1, 10
	s_branch .LBB0_650

; __global__ void __launch_bounds__(512) mega(Params pk) {
;     ...
;     for (int ph = ph_lo; ph < ph_hi; ++ph) {
;         const int l = (ph - 1) / 8, sub = (ph == 0) ? 9 : (((ph - 1) % 8) == 7 ? 8 : (ph - 1) % 8);
;         int nrep = 1;
;     ...
;         if (ph < N_PHASES - 1 && sub == (PROBE % 100)) nrep = 2;
;     ...
;         for (int rep = 0; rep < nrep; ++rep) {
;             const bool dry = (PROBE >= 200) && (rep == 0) && (nrep == 2);
;             if (ph == 0) { const Params p = load_params(lp); phase_prep(p, lds); }
;             else if (ph == N_PHASES - 1) { const Params p = load_params(lp); phase_final(p); }
;             else if (sub == 0 || sub == 5) { const Params p = load_params(lp); phase_norm(p, l, sub == 5); }
;             else if (sub == 2) { const Params p = load_params(lp); phase_mix(p, l, lds); }
;             else { for (int gi = 0; gi < 6; ++gi) { if (!gemm_phase(lds, l, sub, gi, dry)) break; } }
;             if (rep + 1 < nrep) xcd_barrier(xb);
;         }
;         if (ph + 1 < ph_hi) xcd_barrier(xb);
.LBB0_649:
	s_cmpk_lg_u32 s72, 0x100
	s_cbranch_scc1 .LBB0_735
	s_cmp_eq_u32 s16, 2
	s_cbranch_scc1 .Lmy_dp_m0
	s_cmp_eq_u32 s16, 5
	s_cbranch_scc1 .Lmy_dp_m1
	s_cmp_eq_u32 s16, 10
	s_cbranch_scc1 .Lmy_dp_m2
	s_branch .LBB0_735
